# sample item: first 16 cached-key loads hoisted above the gate matvec loop; second 16 issued at score stage start
# speedup vs baseline: 1.0008x; 1.0008x over previous
.LBB0_288:
	s_and_b32 s51, s27, 15
	s_ashr_i32 s18, s22, 4
	s_lshl_b32 s2, s51, 14
	s_and_b32 s50, s22, 15
	s_ashr_i32 s19, s18, 31
	s_add_u32 s16, s18, 0x8000
	s_addc_u32 s17, s19, 0
	s_mul_i32 s0, s16, 0x2c00
	v_readlane_b32 s20, v254, 41
	v_readlane_b32 s84, v254, 7
	s_mul_hi_i32 s1, s16, 0x2c00
	v_readlane_b32 s21, v254, 42
	s_add_u32 s0, s20, s0
	v_readlane_b32 s92, v254, 15
	v_readlane_b32 s93, v254, 16
	v_lshl_or_b32 v12, s50, 6, v0
	s_addc_u32 s1, s21, s1
	s_mul_i32 s52, s18, 0x3000
	v_readlane_b32 s94, v254, 17
	v_readlane_b32 s95, v254, 18
	s_mov_b64 s[64:65], s[92:93]
	v_lshlrev_b32_e32 v2, 1, v12
	s_mul_hi_i32 s53, s18, 0x3000
	s_add_u32 s20, s64, s52
	v_lshl_add_u64 v[14:15], s[0:1], 0, v[2:3]
	global_load_ushort v11, v2, s[0:1] offset:3072
	s_addc_u32 s21, s65, s53
	v_lshlrev_b32_e32 v2, 2, v12
	v_lshl_add_u64 v[16:17], s[20:21], 0, v[2:3]
	v_add_co_u32_e32 v16, vcc, s30, v16
	v_readlane_b32 s85, v254, 8
	s_nop 0
	v_addc_co_u32_e32 v17, vcc, 0, v17, vcc
	global_load_dword v22, v[16:17], off offset:-4096
	global_load_dword v23, v[16:17], off
	v_readlane_b32 s86, v254, 9
	v_readlane_b32 s87, v254, 10
	v_readlane_b32 s88, v254, 11
	v_readlane_b32 s89, v254, 12
	v_readlane_b32 s90, v254, 13
	v_readlane_b32 s91, v254, 14
	v_readlane_b32 s96, v254, 19
	v_readlane_b32 s97, v254, 20
	v_readlane_b32 s98, v254, 21
	v_readlane_b32 s99, v254, 22
	s_mov_b64 s[66:67], s[94:95]
	v_readlane_b32 s84, v254, 23
	v_readlane_b32 s86, v254, 25
	v_readlane_b32 s87, v254, 26
	s_add_u32 s52, s80, s52
	s_addc_u32 s53, s81, s53
	v_lshl_add_u64 v[16:17], s[86:87], 0, v[2:3]
	v_add_co_u32_e32 v18, vcc, s30, v16
	v_lshl_add_u64 v[20:21], s[52:53], 0, v[2:3]
	s_nop 0
	v_addc_co_u32_e32 v19, vcc, 0, v17, vcc
	v_add_co_u32_e32 v16, vcc, s28, v16
	v_readlane_b32 s88, v254, 27
	s_nop 0
	v_addc_co_u32_e32 v17, vcc, 0, v17, vcc
	v_readlane_b32 s89, v254, 28
	global_load_dword v34, v2, s[20:21]
	s_nop 3
	global_load_dword v1, v2, s[88:89]
	global_load_dword v35, v2, s[86:87]
	global_load_dword v36, v[18:19], off offset:-4096
	global_load_dword v37, v[18:19], off
	v_add_co_u32_e32 v18, vcc, s31, v20
	global_load_dword v38, v[16:17], off
	s_nop 0
	v_addc_co_u32_e32 v19, vcc, 0, v21, vcc
	v_add_co_u32_e32 v16, vcc, 0xa4c1000, v20
	v_readlane_b32 s92, v254, 31
	s_nop 0
	v_addc_co_u32_e32 v17, vcc, 0, v21, vcc
	v_add_co_u32_e32 v20, vcc, 0xa4c2000, v20
	v_readlane_b32 s93, v254, 32
	s_nop 0
	v_addc_co_u32_e32 v21, vcc, 0, v21, vcc
	v_readlane_b32 s96, v254, 35
	v_readlane_b32 s97, v254, 36
	s_mov_b64 s[20:21], 0
	v_readlane_b32 s85, v254, 24
	v_readlane_b32 s90, v254, 29
	v_readlane_b32 s91, v254, 30
	v_readlane_b32 s94, v254, 33
	v_readlane_b32 s95, v254, 34
	v_readlane_b32 s98, v254, 37
	v_readlane_b32 s99, v254, 38
	s_waitcnt vmcnt(8)
	v_lshlrev_b32_e32 v11, 16, v11
	global_store_dword v[20:21], v11, off
	s_waitcnt vmcnt(8)
	global_store_dword v[18:19], v22, off
	s_waitcnt vmcnt(8)
	global_store_dword v[16:17], v23, off
	global_load_dword v16, v2, s[92:93]
	s_nop 0
	global_load_dword v17, v2, s[96:97]
	v_lshl_add_u64 v[18:19], v[4:5], 0, s[2:3]
	v_lshl_add_u64 v[20:21], v[6:7], 0, s[2:3]
	v_mov_b32_e32 v2, v30
	s_waitcnt vmcnt(8)
	v_fmac_f32_e32 v1, v34, v35
	s_waitcnt vmcnt(7)
	v_fmac_f32_e32 v1, v22, v36
	s_waitcnt vmcnt(6)
	v_fmac_f32_e32 v1, v23, v37
	s_waitcnt vmcnt(5)
	v_fmac_f32_e32 v1, v38, v11
	v_and_b32_e32 v162, 15, v0
	v_lshrrev_b32_e32 v163, 4, v0
	v_lshlrev_b32_e32 v162, 4, v162
	v_lshl_add_u32 v162, v163, 10, v162
	s_lshl_b32 vcc_lo, s18, 17
	s_lshr_b32 vcc_hi, s50, 2
	s_lshl_b32 vcc_hi, vcc_hi, 8
	s_add_i32 vcc_lo, vcc_lo, vcc_hi
	s_add_i32 vcc_lo, vcc_lo, 0x1000
	v_add_u32_e32 v162, vcc_lo, v162
	v_mov_b32_e32 v163, 0
	v_readlane_b32 vcc_lo, v254, 11
	v_readlane_b32 vcc_hi, v254, 12
	v_mov_b32_e32 v230, 0x2000
	v_mov_b32_e32 v231, 0
	v_lshl_add_u64 v[162:163], vcc, 0, v[162:163]
	global_load_dwordx4 v[164:167], v[162:163], off offset:-4096
	global_load_dwordx4 v[168:171], v[162:163], off
	v_lshl_add_u64 v[162:163], v[162:163], 0, v[230:231]
	global_load_dwordx4 v[172:175], v[162:163], off offset:-4096
	global_load_dwordx4 v[176:179], v[162:163], off
	v_lshl_add_u64 v[162:163], v[162:163], 0, v[230:231]
	global_load_dwordx4 v[180:183], v[162:163], off offset:-4096
	global_load_dwordx4 v[184:187], v[162:163], off
	v_lshl_add_u64 v[162:163], v[162:163], 0, v[230:231]
	global_load_dwordx4 v[188:191], v[162:163], off offset:-4096
	global_load_dwordx4 v[192:195], v[162:163], off
	v_lshl_add_u64 v[162:163], v[162:163], 0, v[230:231]
	global_load_dwordx4 v[196:199], v[162:163], off offset:-4096
	global_load_dwordx4 v[200:203], v[162:163], off
	v_lshl_add_u64 v[162:163], v[162:163], 0, v[230:231]
	global_load_dwordx4 v[204:207], v[162:163], off offset:-4096
	global_load_dwordx4 v[208:211], v[162:163], off
	v_lshl_add_u64 v[162:163], v[162:163], 0, v[230:231]
	global_load_dwordx4 v[212:215], v[162:163], off offset:-4096
	global_load_dwordx4 v[216:219], v[162:163], off
	v_lshl_add_u64 v[162:163], v[162:163], 0, v[230:231]
	global_load_dwordx4 v[220:223], v[162:163], off offset:-4096
	global_load_dwordx4 v[224:227], v[162:163], off
	v_lshl_add_u64 v[162:163], v[162:163], 0, v[230:231]
.LBB0_289:
	v_lshl_add_u64 v[22:23], v[20:21], 0, s[20:21]
	v_lshl_add_u64 v[34:35], v[18:19], 0, s[20:21]
	global_load_dword v36, v[22:23], off
	global_load_dword v38, v[22:23], off offset:256
	global_load_dword v40, v[22:23], off offset:512
	global_load_dword v42, v[22:23], off offset:768
	global_load_dword v44, v[22:23], off offset:1024
	global_load_dword v46, v[22:23], off offset:1280
	global_load_dword v48, v[22:23], off offset:1536
	global_load_dword v50, v[22:23], off offset:1792
	global_load_dword v37, v[34:35], off
	global_load_dword v39, v[34:35], off offset:256
	global_load_dword v41, v[34:35], off offset:512
	global_load_dword v43, v[34:35], off offset:768
	global_load_dword v45, v[34:35], off offset:1024
	global_load_dword v47, v[34:35], off offset:1280
	global_load_dword v49, v[34:35], off offset:1536
	global_load_dword v51, v[34:35], off offset:1792
	global_load_dword v52, v[22:23], off offset:2048
	global_load_dword v54, v[22:23], off offset:2304
	global_load_dword v56, v[22:23], off offset:2560
	global_load_dword v58, v[22:23], off offset:2816
	global_load_dword v60, v[22:23], off offset:3072
	global_load_dword v62, v[22:23], off offset:3328
	global_load_dword v64, v[22:23], off offset:3584
	global_load_dword v66, v[22:23], off offset:3840
	global_load_dword v53, v[34:35], off offset:2048
	global_load_dword v55, v[34:35], off offset:2304
	global_load_dword v57, v[34:35], off offset:2560
	global_load_dword v59, v[34:35], off offset:2816
	global_load_dword v61, v[34:35], off offset:3072
	global_load_dword v63, v[34:35], off offset:3328
	global_load_dword v65, v[34:35], off offset:3584
	global_load_dword v67, v[34:35], off offset:3840
	v_add_co_u32_e32 v22, vcc, s29, v22
	v_add_u32_e32 v11, 0xffffff84, v2
	s_nop 0
	v_addc_co_u32_e32 v23, vcc, 0, v23, vcc
	v_add_co_u32_e32 v34, vcc, s29, v34
	v_add_u32_e32 v99, 0xffffff88, v2
	s_nop 0
	v_addc_co_u32_e32 v35, vcc, 0, v35, vcc
	global_load_dword v68, v[22:23], off
	global_load_dword v70, v[22:23], off offset:256
	global_load_dword v72, v[22:23], off offset:512
	global_load_dword v74, v[22:23], off offset:768
	global_load_dword v76, v[22:23], off offset:1024
	global_load_dword v78, v[22:23], off offset:1280
	global_load_dword v80, v[22:23], off offset:1536
	global_load_dword v82, v[22:23], off offset:1792
	global_load_dword v69, v[34:35], off
	global_load_dword v71, v[34:35], off offset:256
	global_load_dword v73, v[34:35], off offset:512
	global_load_dword v75, v[34:35], off offset:768
	global_load_dword v77, v[34:35], off offset:1024
	global_load_dword v79, v[34:35], off offset:1280
	global_load_dword v81, v[34:35], off offset:1536
	global_load_dword v83, v[34:35], off offset:1792
	global_load_dword v84, v[22:23], off offset:2048
	global_load_dword v86, v[22:23], off offset:2304
	global_load_dword v88, v[22:23], off offset:2560
	global_load_dword v90, v[22:23], off offset:2816
	global_load_dword v92, v[22:23], off offset:3072
	global_load_dword v94, v[22:23], off offset:3328
	global_load_dword v96, v[22:23], off offset:3584
	s_nop 0
	global_load_dword v22, v[22:23], off offset:3840
	s_nop 0
	global_load_dword v85, v[34:35], off offset:2048
	global_load_dword v87, v[34:35], off offset:2304
	global_load_dword v89, v[34:35], off offset:2560
	global_load_dword v91, v[34:35], off offset:2816
	global_load_dword v93, v[34:35], off offset:3072
	global_load_dword v95, v[34:35], off offset:3328
	global_load_dword v97, v[34:35], off offset:3584
	global_load_dword v23, v[34:35], off offset:3840
	ds_bpermute_b32 v98, v11, v1
	v_add_u32_e32 v101, 0xffffff8c, v2
	ds_bpermute_b32 v100, v99, v1
	v_add_u32_e32 v103, 0xffffff90, v2
	ds_bpermute_b32 v102, v101, v1
	v_add_u32_e32 v105, 0xffffff94, v2
	ds_bpermute_b32 v104, v103, v1
	v_add_u32_e32 v107, 0xffffff98, v2
	ds_bpermute_b32 v106, v105, v1
	v_add_u32_e32 v109, 0xffffff9c, v2
	ds_bpermute_b32 v108, v107, v1
	v_add_u32_e32 v111, 0xffffffa0, v2
	ds_bpermute_b32 v110, v109, v1
	v_add_u32_e32 v113, 0xffffffa4, v2
	ds_bpermute_b32 v112, v111, v1
	v_add_u32_e32 v115, 0xffffffa8, v2
	ds_bpermute_b32 v114, v113, v1
	v_add_u32_e32 v117, 0xffffffac, v2
	ds_bpermute_b32 v116, v115, v1
	v_add_u32_e32 v119, 0xffffffb0, v2
	ds_bpermute_b32 v118, v117, v1
	v_add_u32_e32 v121, 0xffffffb4, v2
	ds_bpermute_b32 v120, v119, v1
	v_add_u32_e32 v123, 0xffffffb8, v2
	ds_bpermute_b32 v122, v121, v1
	v_add_u32_e32 v125, 0xffffffbc, v2
	ds_bpermute_b32 v124, v123, v1
	v_subrev_u32_e32 v127, 64, v2
	ds_bpermute_b32 v126, v125, v1
	v_subrev_u32_e32 v129, 60, v2
	ds_bpermute_b32 v128, v127, v1
	v_subrev_u32_e32 v131, 56, v2
	ds_bpermute_b32 v130, v129, v1
	v_subrev_u32_e32 v133, 52, v2
	ds_bpermute_b32 v132, v131, v1
	v_subrev_u32_e32 v35, 48, v2
	ds_bpermute_b32 v134, v133, v1
	v_subrev_u32_e32 v135, 44, v2
	ds_bpermute_b32 v136, v35, v1
	v_subrev_u32_e32 v137, 40, v2
	ds_bpermute_b32 v138, v135, v1
	v_subrev_u32_e32 v139, 36, v2
	ds_bpermute_b32 v140, v137, v1
	v_subrev_u32_e32 v141, 32, v2
	ds_bpermute_b32 v142, v139, v1
	s_waitcnt vmcnt(55) lgkmcnt(14)
	v_pk_fma_f32 v[16:17], v[36:37], v[98:99], v[16:17] op_sel_hi:[1,0,1]
	v_subrev_u32_e32 v143, 28, v2
	s_waitcnt vmcnt(54)
	v_pk_fma_f32 v[16:17], v[38:39], v[100:101], v[16:17] op_sel_hi:[1,0,1]
	ds_bpermute_b32 v146, v141, v1
	s_waitcnt vmcnt(53)
	v_pk_fma_f32 v[16:17], v[40:41], v[102:103], v[16:17] op_sel_hi:[1,0,1]
	v_subrev_u32_e32 v145, 24, v2
	s_waitcnt vmcnt(52)
	v_pk_fma_f32 v[16:17], v[42:43], v[104:105], v[16:17] op_sel_hi:[1,0,1]
	ds_bpermute_b32 v148, v143, v1
	s_waitcnt vmcnt(51)
	v_pk_fma_f32 v[16:17], v[44:45], v[106:107], v[16:17] op_sel_hi:[1,0,1]
	v_subrev_u32_e32 v147, 20, v2
	s_waitcnt vmcnt(50)
	v_pk_fma_f32 v[16:17], v[46:47], v[108:109], v[16:17] op_sel_hi:[1,0,1]
	ds_bpermute_b32 v150, v145, v1
	s_waitcnt vmcnt(49)
	v_pk_fma_f32 v[16:17], v[48:49], v[110:111], v[16:17] op_sel_hi:[1,0,1]
	v_add_u32_e32 v149, -16, v2
	s_waitcnt vmcnt(48)
	v_pk_fma_f32 v[16:17], v[50:51], v[112:113], v[16:17] op_sel_hi:[1,0,1]
	ds_bpermute_b32 v152, v147, v1
	s_waitcnt vmcnt(39)
	v_pk_fma_f32 v[16:17], v[52:53], v[114:115], v[16:17] op_sel_hi:[1,0,1]
	v_add_u32_e32 v151, -12, v2
	s_waitcnt vmcnt(38) lgkmcnt(14)
	v_pk_fma_f32 v[16:17], v[54:55], v[116:117], v[16:17] op_sel_hi:[1,0,1]
	ds_bpermute_b32 v154, v149, v1
	s_waitcnt vmcnt(37)
	v_pk_fma_f32 v[16:17], v[56:57], v[118:119], v[16:17] op_sel_hi:[1,0,1]
	v_add_u32_e32 v153, -8, v2
	s_waitcnt vmcnt(36)
	v_pk_fma_f32 v[16:17], v[58:59], v[120:121], v[16:17] op_sel_hi:[1,0,1]
	ds_bpermute_b32 v156, v151, v1
	s_waitcnt vmcnt(35)
	v_pk_fma_f32 v[16:17], v[60:61], v[122:123], v[16:17] op_sel_hi:[1,0,1]
	v_add_u32_e32 v155, -4, v2
	s_waitcnt vmcnt(34) lgkmcnt(14)
	v_pk_fma_f32 v[16:17], v[62:63], v[124:125], v[16:17] op_sel_hi:[1,0,1]
	ds_bpermute_b32 v158, v153, v1
	s_waitcnt vmcnt(33)
	v_pk_fma_f32 v[16:17], v[64:65], v[126:127], v[16:17] op_sel_hi:[1,0,1]
	ds_bpermute_b32 v160, v155, v1
	s_waitcnt vmcnt(32) lgkmcnt(14)
	v_pk_fma_f32 v[16:17], v[66:67], v[128:129], v[16:17] op_sel_hi:[1,0,1]
	ds_bpermute_b32 v34, v2, v1
	s_waitcnt vmcnt(23)
	v_pk_fma_f32 v[16:17], v[68:69], v[130:131], v[16:17] op_sel_hi:[1,0,1]
	s_add_u32 s20, s20, 0x2000
	s_waitcnt vmcnt(22) lgkmcnt(14)
	v_pk_fma_f32 v[16:17], v[70:71], v[132:133], v[16:17] op_sel_hi:[1,0,1]
	s_addc_u32 s21, s21, 0
	s_waitcnt vmcnt(21) lgkmcnt(13)
	v_pk_fma_f32 v[16:17], v[72:73], v[134:135], v[16:17] op_sel_hi:[1,0,1]
	v_add_u32_e32 v2, 0x80, v2
	s_waitcnt vmcnt(20) lgkmcnt(12)
	v_pk_fma_f32 v[16:17], v[74:75], v[136:137], v[16:17] op_sel_hi:[1,0,1]
	s_cmpk_eq_i32 s20, 0x4000
	s_waitcnt vmcnt(19) lgkmcnt(11)
	v_pk_fma_f32 v[16:17], v[76:77], v[138:139], v[16:17] op_sel_hi:[1,0,1]
	s_waitcnt vmcnt(18) lgkmcnt(10)
	v_pk_fma_f32 v[16:17], v[78:79], v[140:141], v[16:17] op_sel_hi:[1,0,1]
	s_waitcnt vmcnt(17) lgkmcnt(9)
	v_pk_fma_f32 v[16:17], v[80:81], v[142:143], v[16:17] op_sel_hi:[1,0,1]
	s_waitcnt vmcnt(16) lgkmcnt(8)
	v_pk_fma_f32 v[16:17], v[82:83], v[146:147], v[16:17] op_sel_hi:[1,0,1]
	s_waitcnt vmcnt(7) lgkmcnt(7)
	v_pk_fma_f32 v[16:17], v[84:85], v[148:149], v[16:17] op_sel_hi:[1,0,1]
	s_waitcnt vmcnt(6) lgkmcnt(6)
	v_pk_fma_f32 v[16:17], v[86:87], v[150:151], v[16:17] op_sel_hi:[1,0,1]
	s_waitcnt vmcnt(5) lgkmcnt(5)
	v_pk_fma_f32 v[16:17], v[88:89], v[152:153], v[16:17] op_sel_hi:[1,0,1]
	s_waitcnt vmcnt(4) lgkmcnt(4)
	v_pk_fma_f32 v[16:17], v[90:91], v[154:155], v[16:17] op_sel_hi:[1,0,1]
	s_waitcnt vmcnt(3) lgkmcnt(3)
	v_pk_fma_f32 v[16:17], v[92:93], v[156:157], v[16:17] op_sel_hi:[1,0,1]
	s_waitcnt vmcnt(2) lgkmcnt(2)
	v_pk_fma_f32 v[16:17], v[94:95], v[158:159], v[16:17] op_sel_hi:[1,0,1]
	s_waitcnt vmcnt(1) lgkmcnt(1)
	v_pk_fma_f32 v[16:17], v[96:97], v[160:161], v[16:17] op_sel_hi:[1,0,1]
	s_waitcnt vmcnt(0) lgkmcnt(0)
	v_pk_fma_f32 v[16:17], v[22:23], v[34:35], v[16:17] op_sel_hi:[1,0,1]
	s_cbranch_scc0 .LBB0_289
	v_readlane_b32 s84, v254, 23
	v_lshlrev_b32_e32 v2, 2, v12
	v_readlane_b32 s98, v254, 37
	v_readlane_b32 s99, v254, 38
	v_mul_f32_e32 v11, 0xbfb8aa3b, v16
	v_exp_f32_e32 v11, v11
	s_lshl_b32 s51, s51, 6
	v_readlane_b32 s52, v254, 7
	s_lshr_b32 s2, s50, 2
	global_load_dword v18, v2, s[98:99]
	s_lshl_b64 s[20:21], s[18:19], 12
	s_and_b32 s51, s51, 0x300
	v_readlane_b32 s62, v254, 17
	v_readlane_b32 s53, v254, 8
	v_readlane_b32 s63, v254, 18
	s_add_u32 s52, s62, s20
	v_mul_f32_e32 v19, 0xbfb8aa3b, v17
	v_lshlrev_b32_e32 v20, 1, v0
	s_addc_u32 s53, s63, s21
	v_add_f32_e32 v11, 1.0, v11
	v_exp_f32_e32 v21, v19
	v_lshl_or_b32 v19, s2, 7, v20
	global_load_dword v20, v2, s[52:53]
	v_rcp_f32_e32 v22, v11
	v_add_co_u32_e32 v16, vcc, s29, v14
	v_add_f32_e32 v21, 1.0, v21
	s_nop 0
	v_addc_co_u32_e32 v17, vcc, 0, v15, vcc
	v_mul_f32_e32 v22, 0xc1000000, v22
	v_rcp_f32_e32 v21, v21
	s_add_u32 s20, s80, s20
	s_addc_u32 s21, s81, s21
	s_lshl_b32 s18, s18, 7
	v_readlane_b32 s56, v254, 11
	v_readlane_b32 s57, v254, 12
	s_lshl_b32 s2, s2, 8
	v_mov_b32_e32 v126, s24
	v_readlane_b32 s85, v254, 24
	s_ashr_i32 s19, s18, 31
	v_readlane_b32 s86, v254, 25
	v_readlane_b32 s87, v254, 26
	v_readlane_b32 s88, v254, 27
	v_readlane_b32 s89, v254, 28
	v_readlane_b32 s90, v254, 29
	v_readlane_b32 s91, v254, 30
	v_readlane_b32 s92, v254, 31
	v_readlane_b32 s93, v254, 32
	v_readlane_b32 s94, v254, 33
	v_readlane_b32 s95, v254, 34
	v_readlane_b32 s96, v254, 35
	v_readlane_b32 s97, v254, 36
	v_readlane_b32 s54, v254, 9
	v_readlane_b32 s55, v254, 10
	v_readlane_b32 s58, v254, 13
	v_readlane_b32 s59, v254, 14
	v_readlane_b32 s60, v254, 15
	v_readlane_b32 s61, v254, 16
	v_readlane_b32 s64, v254, 19
	v_readlane_b32 s65, v254, 20
	v_readlane_b32 s66, v254, 21
	v_readlane_b32 s67, v254, 22
	s_waitcnt vmcnt(1)
	v_mul_f32_e32 v11, 0xbfb8aa3b, v18
	v_fma_f32 v23, v18, s33, -v11
	v_rndne_f32_e32 v34, v11
	v_fmac_f32_e32 v23, 0xb2a5705f, v18
	v_sub_f32_e32 v11, v11, v34
	v_add_f32_e32 v11, v11, v23
	v_cvt_i32_f32_e32 v34, v34
	v_exp_f32_e32 v23, v11
	global_load_ushort v11, v[16:17], off offset:1024
	global_load_ushort v35, v19, s[0:1] offset:2560
	global_load_ushort v80, v19, s[0:1] offset:2048
	global_load_ushort v36, v[14:15], off
	v_cmp_nlt_f32_e32 vcc, s34, v18
	v_ldexp_f32 v19, v23, v34
	s_nop 0
	v_cndmask_b32_e32 v19, 0, v19, vcc
	v_cmp_ngt_f32_e32 vcc, s35, v18
	s_nop 1
	v_cndmask_b32_e32 v23, v33, v19, vcc
	v_add_f32_e32 v34, 1.0, v23
	v_add_f32_e32 v37, -1.0, v34
	v_frexp_mant_f32_e32 v38, v34
	v_cvt_f64_f32_e32 v[18:19], v34
	v_sub_f32_e32 v39, v37, v34
	v_frexp_exp_i32_f64_e32 v18, v[18:19]
	v_cmp_gt_f32_e32 vcc, s37, v38
	v_sub_f32_e32 v37, v23, v37
	v_add_f32_e32 v19, 1.0, v39
	v_subbrev_co_u32_e32 v18, vcc, 0, v18, vcc
	v_add_f32_e32 v19, v37, v19
	v_sub_u32_e32 v37, 0, v18
	v_cvt_f32_i32_e32 v18, v18
	v_ldexp_f32 v34, v34, v37
	v_ldexp_f32 v19, v19, v37
	v_add_f32_e32 v37, -1.0, v34
	v_add_f32_e32 v38, 1.0, v34
	v_add_f32_e32 v39, 1.0, v37
	v_add_f32_e32 v40, -1.0, v38
	v_sub_f32_e32 v39, v34, v39
	v_sub_f32_e32 v34, v34, v40
	v_mul_f32_e32 v40, 0x3f317218, v18
	v_add_f32_e32 v39, v19, v39
	v_add_f32_e32 v19, v19, v34
	v_fma_f32 v34, v18, s38, -v40
	v_add_f32_e32 v41, v37, v39
	v_add_f32_e32 v42, v38, v19
	v_fmac_f32_e32 v34, 0xb102e308, v18
	v_sub_f32_e32 v18, v37, v41
	v_sub_f32_e32 v37, v38, v42
	v_rcp_f32_e32 v38, v42
	v_add_f32_e32 v43, v40, v34
	v_add_f32_e32 v19, v19, v37
	v_sub_f32_e32 v37, v43, v40
	v_sub_f32_e32 v34, v34, v37
	v_mul_f32_e32 v37, v41, v38
	v_add_f32_e32 v18, v39, v18
	v_mul_f32_e32 v39, v42, v37
	v_fma_f32 v40, v37, v42, -v39
	v_fmac_f32_e32 v40, v37, v19
	v_add_f32_e32 v44, v39, v40
	v_sub_f32_e32 v45, v41, v44
	v_sub_f32_e32 v39, v44, v39
	v_sub_f32_e32 v41, v41, v45
	v_sub_f32_e32 v39, v39, v40
	v_sub_f32_e32 v40, v41, v44
	v_add_f32_e32 v18, v18, v40
	v_add_f32_e32 v18, v39, v18
	v_add_f32_e32 v39, v45, v18
	v_mul_f32_e32 v40, v38, v39
	v_sub_f32_e32 v41, v45, v39
	v_mul_f32_e32 v44, v42, v40
	v_add_f32_e32 v18, v18, v41
	v_add_f32_e32 v41, v37, v40
	v_fma_f32 v42, v40, v42, -v44
	v_sub_f32_e32 v37, v41, v37
	v_fmac_f32_e32 v42, v40, v19
	v_sub_f32_e32 v19, v40, v37
	v_add_f32_e32 v37, v44, v42
	v_sub_f32_e32 v40, v37, v44
	v_sub_f32_e32 v44, v39, v37
	v_sub_f32_e32 v39, v39, v44
	v_sub_f32_e32 v37, v39, v37
	v_sub_f32_e32 v40, v40, v42
	v_add_f32_e32 v18, v18, v37
	v_add_f32_e32 v18, v40, v18
	v_add_f32_e32 v18, v44, v18
	v_mul_f32_e32 v18, v38, v18
	v_add_f32_e32 v18, v19, v18
	v_add_f32_e32 v19, v41, v18
	v_mul_f32_e32 v37, v19, v19
	v_fmamk_f32 v40, v37, 0x3e9b6dac, v31
	v_sub_f32_e32 v38, v19, v41
	v_ldexp_f32 v39, v19, 1
	v_mul_f32_e32 v19, v19, v37
	v_fmaak_f32 v37, v37, v40, 0x3f2aaada
	v_mul_f32_e32 v19, v19, v37
	v_add_f32_e32 v37, v39, v19
	v_sub_f32_e32 v18, v18, v38
	v_sub_f32_e32 v38, v37, v39
	v_ldexp_f32 v18, v18, 1
	v_sub_f32_e32 v19, v19, v38
	v_add_f32_e32 v18, v18, v19
	v_add_f32_e32 v19, v37, v18
	v_sub_f32_e32 v37, v19, v37
	v_add_f32_e32 v38, v43, v19
	v_sub_f32_e32 v18, v18, v37
	v_sub_f32_e32 v37, v38, v43
	v_sub_f32_e32 v39, v38, v37
	v_sub_f32_e32 v19, v19, v37
	v_add_f32_e32 v37, v34, v18
	v_sub_f32_e32 v39, v43, v39
	v_sub_f32_e32 v40, v37, v34
	v_add_f32_e32 v19, v19, v39
	v_sub_f32_e32 v39, v37, v40
	v_sub_f32_e32 v18, v18, v40
	v_sub_f32_e32 v34, v34, v39
	v_add_f32_e32 v19, v37, v19
	v_add_f32_e32 v18, v18, v34
	v_add_f32_e32 v34, v38, v19
	v_sub_f32_e32 v37, v34, v38
	v_sub_f32_e32 v19, v19, v37
	v_add_f32_e32 v18, v18, v19
	v_add_f32_e32 v18, v34, v18
	v_cmp_neq_f32_e32 vcc, s36, v23
	s_nop 1
	v_cndmask_b32_e32 v18, v33, v18, vcc
	v_cmp_lt_f32_e64 vcc, |v23|, s39
	s_nop 1
	v_cndmask_b32_e32 v18, v18, v23, vcc
	v_mul_f32_e32 v18, v22, v18
	v_add_f32_e32 v19, v18, v18
	v_mul_f32_e32 v19, 0x3fb8aa3b, v19
	v_exp_f32_e32 v19, v19
	v_mul_f32_e32 v18, 0x3fb8aa3b, v18
	v_exp_f32_e32 v18, v18
	v_sub_f32_e32 v19, 1.0, v19
	v_max_f32_e32 v19, 0, v19
	v_mul_f32_e32 v22, 0x4f800000, v19
	v_cmp_gt_f32_e32 vcc, s40, v19
	s_nop 1
	v_cndmask_b32_e32 v19, v19, v22, vcc
	v_sqrt_f32_e32 v22, v19
	s_nop 0
	v_add_u32_e32 v23, -1, v22
	v_add_u32_e32 v34, 1, v22
	v_fma_f32 v37, -v23, v22, v19
	v_fma_f32 v38, -v34, v22, v19
	v_cmp_ge_f32_e64 s[0:1], 0, v37
	s_nop 1
	v_cndmask_b32_e64 v22, v22, v23, s[0:1]
	v_cmp_lt_f32_e64 s[0:1], 0, v38
	s_nop 1
	v_cndmask_b32_e64 v22, v22, v34, s[0:1]
	v_mul_f32_e32 v23, 0x37800000, v22
	v_cndmask_b32_e32 v22, v22, v23, vcc
	v_cmp_class_f32_e32 vcc, v19, v32
	s_lshl_b32 s0, s50, 2
	s_nop 0
	v_cndmask_b32_e32 v19, v22, v19, vcc
	v_mul_f32_e32 v19, v21, v19
	v_mul_f32_e32 v34, v1, v19
	s_waitcnt vmcnt(4)
	v_fmac_f32_e32 v34, v20, v18
	v_lshl_add_u64 v[18:19], s[20:21], 0, v[2:3]
	v_add_co_u32_e32 v18, vcc, s41, v18
	s_waitcnt vmcnt(0)
	v_lshlrev_b32_e32 v2, 16, v36
	v_addc_co_u32_e32 v19, vcc, 0, v19, vcc
	global_store_dword v[18:19], v34, off
	v_or_b32_e32 v18, s18, v0
	v_ashrrev_i32_e32 v19, 31, v18
	v_lshlrev_b64 v[18:19], 10, v[18:19]
	v_lshl_add_u64 v[18:19], s[56:57], 0, v[18:19]
	v_lshl_add_u64 v[18:19], v[18:19], 0, s[2:3]
	ds_write_b32 v13, v2
	s_waitcnt lgkmcnt(0)
	v_lshlrev_b32_e32 v1, 16, v80
	v_and_b32_e32 v21, 15, v0
	v_lshrrev_b32_e32 v22, 4, v0
	v_lshl_add_u32 v113, v22, 2, v126
	v_lshl_add_u32 v112, v21, 4, v126
	ds_read_b128 v[116:119], v112
	global_load_dwordx4 v[36:39], v[162:163], off offset:-4096
	global_load_dwordx4 v[40:43], v[162:163], off
	v_lshl_add_u64 v[162:163], v[162:163], 0, v[230:231]
	global_load_dwordx4 v[44:47], v[162:163], off offset:-4096
	global_load_dwordx4 v[48:51], v[162:163], off
	v_lshl_add_u64 v[162:163], v[162:163], 0, v[230:231]
	global_load_dwordx4 v[52:55], v[162:163], off offset:-4096
	global_load_dwordx4 v[56:59], v[162:163], off
	v_lshl_add_u64 v[162:163], v[162:163], 0, v[230:231]
	global_load_dwordx4 v[60:63], v[162:163], off offset:-4096
	global_load_dwordx4 v[64:67], v[162:163], off
	v_lshl_add_u64 v[162:163], v[162:163], 0, v[230:231]
	global_load_dwordx4 v[68:71], v[162:163], off offset:-4096
	global_load_dwordx4 v[72:75], v[162:163], off
	v_lshl_add_u64 v[162:163], v[162:163], 0, v[230:231]
	global_load_dwordx4 v[76:79], v[162:163], off offset:-4096
	global_load_dwordx4 v[80:83], v[162:163], off
	v_lshl_add_u64 v[162:163], v[162:163], 0, v[230:231]
	global_load_dwordx4 v[84:87], v[162:163], off offset:-4096
	global_load_dwordx4 v[88:91], v[162:163], off
	v_lshl_add_u64 v[162:163], v[162:163], 0, v[230:231]
	global_load_dwordx4 v[92:95], v[162:163], off offset:-4096
	global_load_dwordx4 v[96:99], v[162:163], off
	v_mov_b32_e32 v20, s0
	global_load_dword v20, v20, s[84:85]
	s_waitcnt lgkmcnt(0)
	v_mul_f32_e32 v100, v164, v116
	v_mul_f32_e32 v101, v168, v116
	v_mul_f32_e32 v102, v172, v116
	v_mul_f32_e32 v103, v176, v116
	v_fmac_f32_e32 v100, v165, v117
	v_fmac_f32_e32 v101, v169, v117
	v_fmac_f32_e32 v102, v173, v117
	v_fmac_f32_e32 v103, v177, v117
	v_fmac_f32_e32 v100, v166, v118
	v_fmac_f32_e32 v101, v170, v118
	v_fmac_f32_e32 v102, v174, v118
	v_fmac_f32_e32 v103, v178, v118
	v_fmac_f32_e32 v100, v167, v119
	v_fmac_f32_e32 v101, v171, v119
	v_fmac_f32_e32 v102, v175, v119
	v_fmac_f32_e32 v103, v179, v119
	v_add_f32_dpp v100, v100, v100 row_ror:8 row_mask:0xf bank_mask:0xf
	v_add_f32_dpp v101, v101, v101 row_ror:8 row_mask:0xf bank_mask:0xf
	v_add_f32_dpp v102, v102, v102 row_ror:8 row_mask:0xf bank_mask:0xf
	v_add_f32_dpp v103, v103, v103 row_ror:8 row_mask:0xf bank_mask:0xf
	v_add_f32_dpp v100, v100, v100 row_ror:4 row_mask:0xf bank_mask:0xf
	v_add_f32_dpp v101, v101, v101 row_ror:4 row_mask:0xf bank_mask:0xf
	v_add_f32_dpp v102, v102, v102 row_ror:4 row_mask:0xf bank_mask:0xf
	v_add_f32_dpp v103, v103, v103 row_ror:4 row_mask:0xf bank_mask:0xf
	v_add_f32_dpp v100, v100, v100 row_ror:2 row_mask:0xf bank_mask:0xf
	v_add_f32_dpp v101, v101, v101 row_ror:2 row_mask:0xf bank_mask:0xf
	v_add_f32_dpp v102, v102, v102 row_ror:2 row_mask:0xf bank_mask:0xf
	v_add_f32_dpp v103, v103, v103 row_ror:2 row_mask:0xf bank_mask:0xf
	v_add_f32_dpp v100, v100, v100 row_ror:1 row_mask:0xf bank_mask:0xf
	v_add_f32_dpp v101, v101, v101 row_ror:1 row_mask:0xf bank_mask:0xf
	v_add_f32_dpp v102, v102, v102 row_ror:1 row_mask:0xf bank_mask:0xf
	v_add_f32_dpp v103, v103, v103 row_ror:1 row_mask:0xf bank_mask:0xf
	s_nop 1
	ds_write_b32 v113, v100 offset:256
	ds_write_b32 v113, v101 offset:272
	ds_write_b32 v113, v102 offset:288
	ds_write_b32 v113, v103 offset:304
	v_mul_f32_e32 v104, v180, v116
	v_mul_f32_e32 v105, v184, v116
	v_mul_f32_e32 v106, v188, v116
	v_mul_f32_e32 v107, v192, v116
	v_fmac_f32_e32 v104, v181, v117
	v_fmac_f32_e32 v105, v185, v117
	v_fmac_f32_e32 v106, v189, v117
	v_fmac_f32_e32 v107, v193, v117
	v_fmac_f32_e32 v104, v182, v118
	v_fmac_f32_e32 v105, v186, v118
	v_fmac_f32_e32 v106, v190, v118
	v_fmac_f32_e32 v107, v194, v118
	v_fmac_f32_e32 v104, v183, v119
	v_fmac_f32_e32 v105, v187, v119
	v_fmac_f32_e32 v106, v191, v119
	v_fmac_f32_e32 v107, v195, v119
	v_add_f32_dpp v104, v104, v104 row_ror:8 row_mask:0xf bank_mask:0xf
	v_add_f32_dpp v105, v105, v105 row_ror:8 row_mask:0xf bank_mask:0xf
	v_add_f32_dpp v106, v106, v106 row_ror:8 row_mask:0xf bank_mask:0xf
	v_add_f32_dpp v107, v107, v107 row_ror:8 row_mask:0xf bank_mask:0xf
	v_add_f32_dpp v104, v104, v104 row_ror:4 row_mask:0xf bank_mask:0xf
	v_add_f32_dpp v105, v105, v105 row_ror:4 row_mask:0xf bank_mask:0xf
	v_add_f32_dpp v106, v106, v106 row_ror:4 row_mask:0xf bank_mask:0xf
	v_add_f32_dpp v107, v107, v107 row_ror:4 row_mask:0xf bank_mask:0xf
	v_add_f32_dpp v104, v104, v104 row_ror:2 row_mask:0xf bank_mask:0xf
	v_add_f32_dpp v105, v105, v105 row_ror:2 row_mask:0xf bank_mask:0xf
	v_add_f32_dpp v106, v106, v106 row_ror:2 row_mask:0xf bank_mask:0xf
	v_add_f32_dpp v107, v107, v107 row_ror:2 row_mask:0xf bank_mask:0xf
	v_add_f32_dpp v104, v104, v104 row_ror:1 row_mask:0xf bank_mask:0xf
	v_add_f32_dpp v105, v105, v105 row_ror:1 row_mask:0xf bank_mask:0xf
	v_add_f32_dpp v106, v106, v106 row_ror:1 row_mask:0xf bank_mask:0xf
	v_add_f32_dpp v107, v107, v107 row_ror:1 row_mask:0xf bank_mask:0xf
	s_nop 1
	ds_write_b32 v113, v104 offset:320
	ds_write_b32 v113, v105 offset:336
	ds_write_b32 v113, v106 offset:352
	ds_write_b32 v113, v107 offset:368
	v_mul_f32_e32 v100, v196, v116
	v_mul_f32_e32 v101, v200, v116
	v_mul_f32_e32 v102, v204, v116
	v_mul_f32_e32 v103, v208, v116
	v_fmac_f32_e32 v100, v197, v117
	v_fmac_f32_e32 v101, v201, v117
	v_fmac_f32_e32 v102, v205, v117
	v_fmac_f32_e32 v103, v209, v117
	v_fmac_f32_e32 v100, v198, v118
	v_fmac_f32_e32 v101, v202, v118
	v_fmac_f32_e32 v102, v206, v118
	v_fmac_f32_e32 v103, v210, v118
	v_fmac_f32_e32 v100, v199, v119
	v_fmac_f32_e32 v101, v203, v119
	v_fmac_f32_e32 v102, v207, v119
	v_fmac_f32_e32 v103, v211, v119
	v_add_f32_dpp v100, v100, v100 row_ror:8 row_mask:0xf bank_mask:0xf
	v_add_f32_dpp v101, v101, v101 row_ror:8 row_mask:0xf bank_mask:0xf
	v_add_f32_dpp v102, v102, v102 row_ror:8 row_mask:0xf bank_mask:0xf
	v_add_f32_dpp v103, v103, v103 row_ror:8 row_mask:0xf bank_mask:0xf
	v_add_f32_dpp v100, v100, v100 row_ror:4 row_mask:0xf bank_mask:0xf
	v_add_f32_dpp v101, v101, v101 row_ror:4 row_mask:0xf bank_mask:0xf
	v_add_f32_dpp v102, v102, v102 row_ror:4 row_mask:0xf bank_mask:0xf
	v_add_f32_dpp v103, v103, v103 row_ror:4 row_mask:0xf bank_mask:0xf
	v_add_f32_dpp v100, v100, v100 row_ror:2 row_mask:0xf bank_mask:0xf
	v_add_f32_dpp v101, v101, v101 row_ror:2 row_mask:0xf bank_mask:0xf
	v_add_f32_dpp v102, v102, v102 row_ror:2 row_mask:0xf bank_mask:0xf
	v_add_f32_dpp v103, v103, v103 row_ror:2 row_mask:0xf bank_mask:0xf
	v_add_f32_dpp v100, v100, v100 row_ror:1 row_mask:0xf bank_mask:0xf
	v_add_f32_dpp v101, v101, v101 row_ror:1 row_mask:0xf bank_mask:0xf
	v_add_f32_dpp v102, v102, v102 row_ror:1 row_mask:0xf bank_mask:0xf
	v_add_f32_dpp v103, v103, v103 row_ror:1 row_mask:0xf bank_mask:0xf
	s_nop 1
	ds_write_b32 v113, v100 offset:384
	ds_write_b32 v113, v101 offset:400
	ds_write_b32 v113, v102 offset:416
	ds_write_b32 v113, v103 offset:432
	v_mul_f32_e32 v104, v212, v116
	v_mul_f32_e32 v105, v216, v116
	v_mul_f32_e32 v106, v220, v116
	v_mul_f32_e32 v107, v224, v116
	v_fmac_f32_e32 v104, v213, v117
	v_fmac_f32_e32 v105, v217, v117
	v_fmac_f32_e32 v106, v221, v117
	v_fmac_f32_e32 v107, v225, v117
	v_fmac_f32_e32 v104, v214, v118
	v_fmac_f32_e32 v105, v218, v118
	v_fmac_f32_e32 v106, v222, v118
	v_fmac_f32_e32 v107, v226, v118
	v_fmac_f32_e32 v104, v215, v119
	v_fmac_f32_e32 v105, v219, v119
	v_fmac_f32_e32 v106, v223, v119
	v_fmac_f32_e32 v107, v227, v119
	v_add_f32_dpp v104, v104, v104 row_ror:8 row_mask:0xf bank_mask:0xf
	v_add_f32_dpp v105, v105, v105 row_ror:8 row_mask:0xf bank_mask:0xf
	v_add_f32_dpp v106, v106, v106 row_ror:8 row_mask:0xf bank_mask:0xf
	v_add_f32_dpp v107, v107, v107 row_ror:8 row_mask:0xf bank_mask:0xf
	v_add_f32_dpp v104, v104, v104 row_ror:4 row_mask:0xf bank_mask:0xf
	v_add_f32_dpp v105, v105, v105 row_ror:4 row_mask:0xf bank_mask:0xf
	v_add_f32_dpp v106, v106, v106 row_ror:4 row_mask:0xf bank_mask:0xf
	v_add_f32_dpp v107, v107, v107 row_ror:4 row_mask:0xf bank_mask:0xf
	v_add_f32_dpp v104, v104, v104 row_ror:2 row_mask:0xf bank_mask:0xf
	v_add_f32_dpp v105, v105, v105 row_ror:2 row_mask:0xf bank_mask:0xf
	v_add_f32_dpp v106, v106, v106 row_ror:2 row_mask:0xf bank_mask:0xf
	v_add_f32_dpp v107, v107, v107 row_ror:2 row_mask:0xf bank_mask:0xf
	v_add_f32_dpp v104, v104, v104 row_ror:1 row_mask:0xf bank_mask:0xf
	v_add_f32_dpp v105, v105, v105 row_ror:1 row_mask:0xf bank_mask:0xf
	v_add_f32_dpp v106, v106, v106 row_ror:1 row_mask:0xf bank_mask:0xf
	v_add_f32_dpp v107, v107, v107 row_ror:1 row_mask:0xf bank_mask:0xf
	s_nop 1
	ds_write_b32 v113, v104 offset:448
	ds_write_b32 v113, v105 offset:464
	ds_write_b32 v113, v106 offset:480
	ds_write_b32 v113, v107 offset:496
	s_waitcnt vmcnt(13)
	v_mul_f32_e32 v100, v36, v116
	v_mul_f32_e32 v101, v40, v116
	v_mul_f32_e32 v102, v44, v116
	v_mul_f32_e32 v103, v48, v116
	v_fmac_f32_e32 v100, v37, v117
	v_fmac_f32_e32 v101, v41, v117
	v_fmac_f32_e32 v102, v45, v117
	v_fmac_f32_e32 v103, v49, v117
	v_fmac_f32_e32 v100, v38, v118
	v_fmac_f32_e32 v101, v42, v118
	v_fmac_f32_e32 v102, v46, v118
	v_fmac_f32_e32 v103, v50, v118
	v_fmac_f32_e32 v100, v39, v119
	v_fmac_f32_e32 v101, v43, v119
	v_fmac_f32_e32 v102, v47, v119
	v_fmac_f32_e32 v103, v51, v119
	v_add_f32_dpp v100, v100, v100 row_ror:8 row_mask:0xf bank_mask:0xf
	v_add_f32_dpp v101, v101, v101 row_ror:8 row_mask:0xf bank_mask:0xf
	v_add_f32_dpp v102, v102, v102 row_ror:8 row_mask:0xf bank_mask:0xf
	v_add_f32_dpp v103, v103, v103 row_ror:8 row_mask:0xf bank_mask:0xf
	v_add_f32_dpp v100, v100, v100 row_ror:4 row_mask:0xf bank_mask:0xf
	v_add_f32_dpp v101, v101, v101 row_ror:4 row_mask:0xf bank_mask:0xf
	v_add_f32_dpp v102, v102, v102 row_ror:4 row_mask:0xf bank_mask:0xf
	v_add_f32_dpp v103, v103, v103 row_ror:4 row_mask:0xf bank_mask:0xf
	v_add_f32_dpp v100, v100, v100 row_ror:2 row_mask:0xf bank_mask:0xf
	v_add_f32_dpp v101, v101, v101 row_ror:2 row_mask:0xf bank_mask:0xf
	v_add_f32_dpp v102, v102, v102 row_ror:2 row_mask:0xf bank_mask:0xf
	v_add_f32_dpp v103, v103, v103 row_ror:2 row_mask:0xf bank_mask:0xf
	v_add_f32_dpp v100, v100, v100 row_ror:1 row_mask:0xf bank_mask:0xf
	v_add_f32_dpp v101, v101, v101 row_ror:1 row_mask:0xf bank_mask:0xf
	v_add_f32_dpp v102, v102, v102 row_ror:1 row_mask:0xf bank_mask:0xf
	v_add_f32_dpp v103, v103, v103 row_ror:1 row_mask:0xf bank_mask:0xf
	s_nop 1
	ds_write_b32 v113, v100 offset:512
	ds_write_b32 v113, v101 offset:528
	ds_write_b32 v113, v102 offset:544
	ds_write_b32 v113, v103 offset:560
	s_waitcnt vmcnt(9)
	v_mul_f32_e32 v104, v52, v116
	v_mul_f32_e32 v105, v56, v116
	v_mul_f32_e32 v106, v60, v116
	v_mul_f32_e32 v107, v64, v116
	v_fmac_f32_e32 v104, v53, v117
	v_fmac_f32_e32 v105, v57, v117
	v_fmac_f32_e32 v106, v61, v117
	v_fmac_f32_e32 v107, v65, v117
	v_fmac_f32_e32 v104, v54, v118
	v_fmac_f32_e32 v105, v58, v118
	v_fmac_f32_e32 v106, v62, v118
	v_fmac_f32_e32 v107, v66, v118
	v_fmac_f32_e32 v104, v55, v119
	v_fmac_f32_e32 v105, v59, v119
	v_fmac_f32_e32 v106, v63, v119
	v_fmac_f32_e32 v107, v67, v119
	v_add_f32_dpp v104, v104, v104 row_ror:8 row_mask:0xf bank_mask:0xf
	v_add_f32_dpp v105, v105, v105 row_ror:8 row_mask:0xf bank_mask:0xf
	v_add_f32_dpp v106, v106, v106 row_ror:8 row_mask:0xf bank_mask:0xf
	v_add_f32_dpp v107, v107, v107 row_ror:8 row_mask:0xf bank_mask:0xf
	v_add_f32_dpp v104, v104, v104 row_ror:4 row_mask:0xf bank_mask:0xf
	v_add_f32_dpp v105, v105, v105 row_ror:4 row_mask:0xf bank_mask:0xf
	v_add_f32_dpp v106, v106, v106 row_ror:4 row_mask:0xf bank_mask:0xf
	v_add_f32_dpp v107, v107, v107 row_ror:4 row_mask:0xf bank_mask:0xf
	v_add_f32_dpp v104, v104, v104 row_ror:2 row_mask:0xf bank_mask:0xf
	v_add_f32_dpp v105, v105, v105 row_ror:2 row_mask:0xf bank_mask:0xf
	v_add_f32_dpp v106, v106, v106 row_ror:2 row_mask:0xf bank_mask:0xf
	v_add_f32_dpp v107, v107, v107 row_ror:2 row_mask:0xf bank_mask:0xf
	v_add_f32_dpp v104, v104, v104 row_ror:1 row_mask:0xf bank_mask:0xf
	v_add_f32_dpp v105, v105, v105 row_ror:1 row_mask:0xf bank_mask:0xf
	v_add_f32_dpp v106, v106, v106 row_ror:1 row_mask:0xf bank_mask:0xf
	v_add_f32_dpp v107, v107, v107 row_ror:1 row_mask:0xf bank_mask:0xf
	s_nop 1
	ds_write_b32 v113, v104 offset:576
	ds_write_b32 v113, v105 offset:592
	ds_write_b32 v113, v106 offset:608
	ds_write_b32 v113, v107 offset:624
	s_waitcnt vmcnt(5)
	v_mul_f32_e32 v100, v68, v116
	v_mul_f32_e32 v101, v72, v116
	v_mul_f32_e32 v102, v76, v116
	v_mul_f32_e32 v103, v80, v116
	v_fmac_f32_e32 v100, v69, v117
	v_fmac_f32_e32 v101, v73, v117
	v_fmac_f32_e32 v102, v77, v117
	v_fmac_f32_e32 v103, v81, v117
	v_fmac_f32_e32 v100, v70, v118
	v_fmac_f32_e32 v101, v74, v118
	v_fmac_f32_e32 v102, v78, v118
	v_fmac_f32_e32 v103, v82, v118
	v_fmac_f32_e32 v100, v71, v119
	v_fmac_f32_e32 v101, v75, v119
	v_fmac_f32_e32 v102, v79, v119
	v_fmac_f32_e32 v103, v83, v119
	v_add_f32_dpp v100, v100, v100 row_ror:8 row_mask:0xf bank_mask:0xf
	v_add_f32_dpp v101, v101, v101 row_ror:8 row_mask:0xf bank_mask:0xf
	v_add_f32_dpp v102, v102, v102 row_ror:8 row_mask:0xf bank_mask:0xf
	v_add_f32_dpp v103, v103, v103 row_ror:8 row_mask:0xf bank_mask:0xf
	v_add_f32_dpp v100, v100, v100 row_ror:4 row_mask:0xf bank_mask:0xf
	v_add_f32_dpp v101, v101, v101 row_ror:4 row_mask:0xf bank_mask:0xf
	v_add_f32_dpp v102, v102, v102 row_ror:4 row_mask:0xf bank_mask:0xf
	v_add_f32_dpp v103, v103, v103 row_ror:4 row_mask:0xf bank_mask:0xf
	v_add_f32_dpp v100, v100, v100 row_ror:2 row_mask:0xf bank_mask:0xf
	v_add_f32_dpp v101, v101, v101 row_ror:2 row_mask:0xf bank_mask:0xf
	v_add_f32_dpp v102, v102, v102 row_ror:2 row_mask:0xf bank_mask:0xf
	v_add_f32_dpp v103, v103, v103 row_ror:2 row_mask:0xf bank_mask:0xf
	v_add_f32_dpp v100, v100, v100 row_ror:1 row_mask:0xf bank_mask:0xf
	v_add_f32_dpp v101, v101, v101 row_ror:1 row_mask:0xf bank_mask:0xf
	v_add_f32_dpp v102, v102, v102 row_ror:1 row_mask:0xf bank_mask:0xf
	v_add_f32_dpp v103, v103, v103 row_ror:1 row_mask:0xf bank_mask:0xf
	s_nop 1
	ds_write_b32 v113, v100 offset:640
	ds_write_b32 v113, v101 offset:656
	ds_write_b32 v113, v102 offset:672
	ds_write_b32 v113, v103 offset:688
	s_waitcnt vmcnt(1)
	v_mul_f32_e32 v104, v84, v116
	v_mul_f32_e32 v105, v88, v116
	v_mul_f32_e32 v106, v92, v116
	v_mul_f32_e32 v107, v96, v116
	v_fmac_f32_e32 v104, v85, v117
	v_fmac_f32_e32 v105, v89, v117
	v_fmac_f32_e32 v106, v93, v117
	v_fmac_f32_e32 v107, v97, v117
	v_fmac_f32_e32 v104, v86, v118
	v_fmac_f32_e32 v105, v90, v118
	v_fmac_f32_e32 v106, v94, v118
	v_fmac_f32_e32 v107, v98, v118
	v_fmac_f32_e32 v104, v87, v119
	v_fmac_f32_e32 v105, v91, v119
	v_fmac_f32_e32 v106, v95, v119
	v_fmac_f32_e32 v107, v99, v119
	v_add_f32_dpp v104, v104, v104 row_ror:8 row_mask:0xf bank_mask:0xf
	v_add_f32_dpp v105, v105, v105 row_ror:8 row_mask:0xf bank_mask:0xf
	v_add_f32_dpp v106, v106, v106 row_ror:8 row_mask:0xf bank_mask:0xf
	v_add_f32_dpp v107, v107, v107 row_ror:8 row_mask:0xf bank_mask:0xf
	v_add_f32_dpp v104, v104, v104 row_ror:4 row_mask:0xf bank_mask:0xf
	v_add_f32_dpp v105, v105, v105 row_ror:4 row_mask:0xf bank_mask:0xf
	v_add_f32_dpp v106, v106, v106 row_ror:4 row_mask:0xf bank_mask:0xf
	v_add_f32_dpp v107, v107, v107 row_ror:4 row_mask:0xf bank_mask:0xf
	v_add_f32_dpp v104, v104, v104 row_ror:2 row_mask:0xf bank_mask:0xf
	v_add_f32_dpp v105, v105, v105 row_ror:2 row_mask:0xf bank_mask:0xf
	v_add_f32_dpp v106, v106, v106 row_ror:2 row_mask:0xf bank_mask:0xf
	v_add_f32_dpp v107, v107, v107 row_ror:2 row_mask:0xf bank_mask:0xf
	v_add_f32_dpp v104, v104, v104 row_ror:1 row_mask:0xf bank_mask:0xf
	v_add_f32_dpp v105, v105, v105 row_ror:1 row_mask:0xf bank_mask:0xf
	v_add_f32_dpp v106, v106, v106 row_ror:1 row_mask:0xf bank_mask:0xf
	v_add_f32_dpp v107, v107, v107 row_ror:1 row_mask:0xf bank_mask:0xf
	s_nop 1
	ds_write_b32 v113, v104 offset:704
	ds_write_b32 v113, v105 offset:720
	ds_write_b32 v113, v106 offset:736
	ds_write_b32 v113, v107 offset:752
	s_waitcnt lgkmcnt(0)
	ds_read_b32 v19, v13 offset:256
	ds_read_b32 v18, v13 offset:512
	s_waitcnt lgkmcnt(0)
	v_mul_f32_e32 v22, 0x3e000000, v19
	v_mul_f32_e32 v23, 0x3e000000, v18
	v_max_f32_e32 v22, v22, v23
	ds_bpermute_b32 v23, v24, v22
	v_mul_f32_e32 v21, v1, v2
	ds_bpermute_b32 v21, v24, v21
	s_lshl_b64 s[0:1], s[18:19], 10
	s_or_b32 s0, s0, s51
	s_waitcnt lgkmcnt(1)
	v_max_f32_e32 v23, v23, v23
	v_max_f32_e32 v22, v22, v23
	s_waitcnt lgkmcnt(0)
	v_fmac_f32_e32 v21, v1, v2
	ds_bpermute_b32 v23, v25, v22
	ds_bpermute_b32 v2, v25, v21
	s_movk_i32 s19, 0xfe00
	s_waitcnt lgkmcnt(1)
	v_max_f32_e32 v23, v23, v23
	s_waitcnt lgkmcnt(0)
	v_add_f32_e32 v2, v21, v2
	v_max_f32_e32 v22, v22, v23
	ds_bpermute_b32 v21, v26, v2
	ds_bpermute_b32 v23, v26, v22
	s_waitcnt lgkmcnt(1)
	v_add_f32_e32 v2, v2, v21
	s_waitcnt lgkmcnt(0)
	v_max_f32_e32 v23, v23, v23
	ds_bpermute_b32 v21, v27, v2
	v_max_f32_e32 v22, v22, v23
	ds_bpermute_b32 v23, v27, v22
	s_waitcnt lgkmcnt(1)
	v_add_f32_e32 v2, v2, v21
	ds_bpermute_b32 v21, v28, v2
	s_waitcnt lgkmcnt(1)
	v_max_f32_e32 v23, v23, v23
	v_max_f32_e32 v22, v22, v23
	ds_bpermute_b32 v23, v28, v22
	s_waitcnt lgkmcnt(1)
	v_add_f32_e32 v2, v2, v21
	ds_bpermute_b32 v21, v29, v2
	s_waitcnt vmcnt(0)
	v_max_f32_e32 v36, v20, v20
	s_waitcnt lgkmcnt(1)
	v_max_f32_e32 v23, v23, v23
	v_max_f32_e32 v22, v22, v23
	ds_bpermute_b32 v23, v29, v22
	s_waitcnt lgkmcnt(1)
	v_add_f32_e32 v21, v2, v21
	v_mul_f32_e32 v2, 0x3e000000, v21
	v_max_f32_e32 v2, v2, v36
	s_waitcnt lgkmcnt(0)
	v_max3_f32 v22, v22, v23, v2
	v_fma_f32 v2, v19, s43, -v22
	v_mul_f32_e32 v2, 0x3fb8aa3b, v2
	v_exp_f32_e32 v19, v2
	v_fma_f32 v2, v18, s43, -v22
	v_mul_f32_e32 v2, 0x3fb8aa3b, v2
	v_exp_f32_e32 v18, v2
	v_fma_f32 v21, v21, s43, -v22
	v_mul_f32_e32 v21, 0x3fb8aa3b, v21
	v_add_f32_e32 v2, v19, v18
	ds_bpermute_b32 v23, v24, v2
	ds_write2st64_b32 v13, v19, v18 offset0:1 offset1:2
	s_waitcnt lgkmcnt(0)
	v_lshl_add_u64 v[18:19], v[8:9], 0, s[0:1]
	s_waitcnt lgkmcnt(1)
	v_add_f32_e32 v2, v2, v23
	ds_bpermute_b32 v23, v25, v2
	s_waitcnt lgkmcnt(0)
	v_add_f32_e32 v2, v2, v23
	ds_bpermute_b32 v23, v26, v2
	s_waitcnt lgkmcnt(0)
	v_add_f32_e32 v2, v2, v23
	ds_bpermute_b32 v23, v27, v2
	s_waitcnt lgkmcnt(0)
	v_add_f32_e32 v36, v2, v23
	ds_bpermute_b32 v37, v28, v36
	v_lshlrev_b32_e32 v2, 16, v35
	v_exp_f32_e32 v23, v21
	s_waitcnt lgkmcnt(0)
	v_add_f32_e32 v35, v36, v37
	ds_bpermute_b32 v36, v29, v35
	v_mul_f32_e32 v21, v23, v2
